# phases D/E tile order: blocks of one XCD share activation row tiles (8 col tiles x 8 row tiles per XCD round) for L2 reuse
# speedup vs baseline: 1.0298x; 1.0298x over previous
; #define LAS __attribute__((address_space(3)))
; __device__ __forceinline__ unsigned xb_ld(unsigned* p)              { return __hip_atomic_load(p, __ATOMIC_RELAXED, __HIP_MEMORY_SCOPE_AGENT); }
; __device__ __forceinline__ void xcd_barrier_complete(unsigned* bar, unsigned x, unsigned& nloc, unsigned& nx) {
;     const unsigned G = gridDim.x * gridDim.y * gridDim.z;
;     unsigned sum, cnt, mine, sp = 0u;
;     for (;;) {
;         sum = 0u; cnt = 0u; mine = 0u;
; #pragma unroll
;         for (unsigned j = 0; j < 16; ++j) { const unsigned c = xb_ld(&bar[XB_XCNT(j)]); sum += c; cnt += (c > 0u) ? 1u : 0u; mine = (j == x) ? c : mine; }
;         if (sum == G) break;
;         __builtin_amdgcn_s_sleep(1);
;         if ((++sp & 255u) == 0u) { if (xb_ld(&bar[XB_TMO])) break; if (sp > XB_SPIN_CAP) { atomicAdd(&bar[XB_TMO], 1u); break; } }
;     }
;     nloc = mine > 0u ? mine : 1u; nx = cnt > 0u ? cnt : 1u;
; __global__ void __launch_bounds__(256, 2) fwd_megakernel(Params p) {
;     ...
;   XcdBarrier xb = xcd_barrier_post((unsigned*)(p.ws + W_BAR), (volatile LAS unsigned*)&xb_words);
;   if (threadIdx.x == 0) sh_xinfo[0] = (int)atomicAdd((unsigned*)(p.ws + W_CTR) + 128 + xb.x, 1u);
;   prep_phase(fresh(p), smem);
;   if (p.out == nullptr) grid.sync();
;   xcd_barrier(xb);
;   if (threadIdx.x == 0) {
;     unsigned* bar = (unsigned*)(p.ws + W_BAR);
;     int na = 0, ia = 0, nloc = 1;
;     for (unsigned j = 0; j < 16; ++j) {
;       const unsigned cj = xb_ld(&bar[XB_XCNT(j)]);
;       if (cj > 0u) { if (j < xb.x) ++ia; ++na; }
;       if (j == xb.x) nloc = (int)cj;
;     }
;     sh_xinfo[1] = nloc > 0 ? nloc : 1; sh_xinfo[2] = ia; sh_xinfo[3] = na > 0 ? na : 1;
;   }
;   __syncthreads();
.LBB0_191:
	s_or_b64 exec, exec, s[22:23]
	v_readlane_b32 s8, v249, 0
	v_readlane_b32 s9, v249, 1
	s_add_u32 s0, s8, 0x1200
	s_addc_u32 s1, s9, 0
	v_readlane_b32 s10, v249, 2
	v_readlane_b32 s11, v249, 3
	v_writelane_b32 v249, s0, 59
	s_mov_b32 s91, 0
	v_mov_b32_e32 v129, 0
	v_writelane_b32 v249, s1, 60
	s_add_u32 s0, s8, 0x1400
	s_addc_u32 s1, s9, 0
	v_writelane_b32 v249, s0, 61
	v_mov_b32_e32 v160, 0x3ecc95a3
	v_mov_b32_e32 v161, 0x260
	v_writelane_b32 v249, s1, 62
	s_add_u32 s0, s8, 0x1500
	s_addc_u32 s1, s9, 0
	v_writelane_b32 v249, s0, 63
	v_mov_b32_e32 v162, 0xffff
	v_readlane_b32 s28, v249, 54
	v_writelane_b32 v250, s1, 0
	s_add_u32 s0, s8, 0x1600
	s_addc_u32 s1, s9, 0
	v_writelane_b32 v250, s0, 1
	v_readlane_b32 s29, v249, 55
	v_mov_b32_e32 v163, 0x358637bd
	v_writelane_b32 v250, s1, 2
	s_add_u32 s0, s8, 0x1700
	s_addc_u32 s1, s9, 0
	v_writelane_b32 v250, s0, 3
	v_mbcnt_hi_u32_b32 v164, -1, v6
	v_mov_b32_e32 v165, 0xc480000
	v_writelane_b32 v250, s1, 4
	s_add_u32 s0, s8, 0x1800
	s_addc_u32 s1, s9, 0
	v_writelane_b32 v250, s0, 5
	v_mov_b32_e32 v166, 0xd4d4000
	v_mov_b64_e32 v[130:131], 0x800
	v_writelane_b32 v250, s1, 6
	s_add_u32 s0, s8, 0x1900
	s_addc_u32 s1, s9, 0
	v_writelane_b32 v250, s0, 7
	v_mov_b32_e32 v167, 0x4400000
	v_mov_b32_e32 v168, 0xccd4000
	v_writelane_b32 v250, s1, 8
	s_add_u32 s0, s8, 0x1a00
	s_addc_u32 s1, s9, 0
	v_writelane_b32 v250, s0, 9
	v_mov_b32_e32 v169, 0x80
	v_mov_b32_e32 v170, 0x1000
	v_writelane_b32 v250, s1, 10
	s_add_u32 s0, s8, 0x1b00
	s_addc_u32 s1, s9, 0
	v_writelane_b32 v250, s0, 11
	v_mov_b32_e32 v171, 0x2000
	v_mov_b32_e32 v172, 0x3000
	v_writelane_b32 v250, s1, 12
	s_add_u32 s0, s8, 0x1c00
	s_addc_u32 s1, s9, 0
	v_writelane_b32 v250, s0, 13
	v_mov_b32_e32 v173, 0x4000
	v_mov_b32_e32 v174, 0x5000
	v_writelane_b32 v250, s1, 14
	s_add_u32 s0, s8, 0x1d00
	s_addc_u32 s1, s9, 0
	v_writelane_b32 v250, s0, 15
	v_mov_b32_e32 v175, 0x6000
	v_mov_b32_e32 v176, 0x7000
	v_writelane_b32 v250, s1, 16
	s_add_u32 s0, s8, 0x1e00
	s_addc_u32 s1, s9, 0
	v_writelane_b32 v250, s0, 17
	v_mov_b32_e32 v177, 0x7f800000
	v_mov_b32_e32 v178, 0x7fc00000
	v_writelane_b32 v250, s1, 18
	s_add_u32 s0, s8, 0x1f00
	s_addc_u32 s1, s9, 0
	v_writelane_b32 v250, s0, 19
	v_mov_b32_e32 v179, 0xff800000
	s_movk_i32 s78, 0x80
	v_writelane_b32 v250, s1, 20
	s_add_u32 s0, s8, 0x2000
	s_addc_u32 s1, s9, 0
	v_writelane_b32 v250, s0, 21
	s_movk_i32 s79, 0x4440
	s_movk_i32 s82, 0x4040
	v_writelane_b32 v250, s1, 22
	s_add_u32 s0, s8, 0x2100
	s_addc_u32 s1, s9, 0
	v_writelane_b32 v250, s0, 23
	s_movk_i32 s92, 0x1010
	s_movk_i32 s83, 0x1080
	v_writelane_b32 v250, s1, 24
	s_add_u32 s0, s8, 0x2200
	s_addc_u32 s1, s9, 0
	v_writelane_b32 v250, s0, 25
	s_movk_i32 s86, 0x210
	s_mov_b32 s93, 0xfea1000
	v_writelane_b32 v250, s1, 26
	s_add_u32 s0, s8, 0x2300
	s_addc_u32 s1, s9, 0
	v_writelane_b32 v250, s0, 27
	s_cmp_eq_u32 s46, 15
	s_mov_b32 s94, 0x800000
	v_writelane_b32 v250, s1, 28
	s_cselect_b64 s[0:1], -1, 0
	v_writelane_b32 v250, s0, 29
	s_cmp_eq_u32 s46, 14
	s_waitcnt lgkmcnt(0)
	v_writelane_b32 v250, s1, 30
	s_cselect_b64 s[0:1], -1, 0
	v_writelane_b32 v250, s0, 31
	s_cmp_eq_u32 s46, 13
	s_barrier
; __device__ __forceinline__ unsigned xb_ld(unsigned* p)              { return __hip_atomic_load(p, __ATOMIC_RELAXED, __HIP_MEMORY_SCOPE_AGENT); }
; __device__ __forceinline__ unsigned xb_add(unsigned* p, unsigned v) { return __hip_atomic_fetch_add(p, v, __ATOMIC_RELAXED, __HIP_MEMORY_SCOPE_AGENT); }
; DI void phase_merge(const Params& p, int layer, char*) {
;   constexpr int NTM = MPAD / 128, NTN = 8, NT = NTM * NTN;
;   const int G = gridDim.x;
;   const int nfull = (NT / G) * G, rem = NT - nfull;
;   const bool split = rem > 0 && 2 * rem <= G;
;   const int lim = split ? nfull : NT;
;   const bool cv = (layer == 0);
;   if (cv && (blockIdx.x & 1)) convert_cache(p, 1, smem);
;   bool first = true;
;   for (int tile = blockIdx.x; tile < lim; tile += G) {
;     const int tn = tile / NTM, tm = tile % NTM;
;     const int t2 = tile + G;
;     const bool hasNext = t2 < lim;
;     merge_tile<4>(p, layer, tm * 128, tn * 128, first, hasNext, (t2 % NTM) * 128, (t2 / NTM) * 128);
;   }
;   if (split && (int)blockIdx.x < 2 * rem) {
;     const int tile = nfull + ((int)blockIdx.x >> 1), half = blockIdx.x & 1;
;     const int tn = tile / NTM, tm = tile % NTM;
; __device__ __forceinline__ void xcd_barrier_complete(unsigned* bar, unsigned x, unsigned& nloc, unsigned& nx) {
;     ...
;         for (unsigned j = 0; j < 16; ++j) { const unsigned c = xb_ld(&bar[XB_XCNT(j)]); sum += c; cnt += (c > 0u) ? 1u : 0u; mine = (j == x) ? c : mine; }
;         if (sum == G) break;
;         __builtin_amdgcn_s_sleep(1);
;         if ((++sp & 255u) == 0u) { if (xb_ld(&bar[XB_TMO])) break; if (sp > XB_SPIN_CAP) { atomicAdd(&bar[XB_TMO], 1u); break; } }
;     }
;     nloc = mine > 0u ? mine : 1u; nx = cnt > 0u ? cnt : 1u;
; }
; __device__ __forceinline__ void xcd_barrier(const XcdBarrier& b) {
;     asm volatile("s_waitcnt vmcnt(0)" ::: "memory");
;     __syncthreads();
;     if (threadIdx.x == 0) {
;         unsigned* bar = b.bar;
;         __builtin_amdgcn_s_waitcnt(0);
;         unsigned nloc = b.st[0], nx = b.st[1];
;         if (nloc == 0u) { xcd_barrier_complete(bar, b.x, nloc, nx); b.st[0] = nloc; b.st[1] = nx; }
;         const unsigned old = xb_add(&bar[XB_XSUB(b.x)], 1u);
	v_writelane_b32 v250, s1, 32
	s_cselect_b64 s[0:1], -1, 0
	v_writelane_b32 v250, s0, 33
	s_cmp_eq_u32 s46, 12
	s_nop 0
	v_writelane_b32 v250, s1, 34
	s_cselect_b64 s[0:1], -1, 0
	v_writelane_b32 v250, s0, 35
	s_cmp_eq_u32 s46, 11
	s_nop 0
	v_writelane_b32 v250, s1, 36
	s_cselect_b64 s[0:1], -1, 0
	v_writelane_b32 v250, s0, 37
	s_cmp_eq_u32 s46, 10
	s_nop 0
	v_writelane_b32 v250, s1, 38
	s_cselect_b64 s[0:1], -1, 0
	v_writelane_b32 v250, s0, 39
	s_cmp_eq_u32 s46, 9
	s_nop 0
	v_writelane_b32 v250, s1, 40
	s_cselect_b64 s[0:1], -1, 0
	v_writelane_b32 v250, s0, 41
	s_cmp_eq_u32 s46, 8
	s_nop 0
	v_writelane_b32 v250, s1, 42
	s_cselect_b64 s[0:1], -1, 0
	v_writelane_b32 v250, s0, 43
	s_cmp_eq_u32 s46, 7
	s_nop 0
	v_writelane_b32 v250, s1, 44
	s_cselect_b64 s[0:1], -1, 0
	v_writelane_b32 v250, s0, 45
	s_cmp_eq_u32 s46, 6
	s_nop 0
	v_writelane_b32 v250, s1, 46
	s_cselect_b64 s[0:1], -1, 0
	v_writelane_b32 v250, s0, 47
	s_cmp_eq_u32 s46, 5
	s_nop 0
	v_writelane_b32 v250, s1, 48
	s_cselect_b64 s[0:1], -1, 0
	v_writelane_b32 v250, s0, 49
	s_cmp_eq_u32 s46, 4
	s_nop 0
	v_writelane_b32 v250, s1, 50
	s_cselect_b64 s[0:1], -1, 0
	v_writelane_b32 v250, s0, 51
	s_cmp_eq_u32 s46, 3
	s_nop 0
	v_writelane_b32 v250, s1, 52
	s_cselect_b64 s[0:1], -1, 0
	v_writelane_b32 v250, s0, 53
	s_cmp_eq_u32 s46, 2
	s_nop 0
	v_writelane_b32 v250, s1, 54
	s_cselect_b64 s[0:1], -1, 0
	v_writelane_b32 v250, s0, 55
	s_cmp_eq_u32 s46, 1
	s_nop 0
	v_writelane_b32 v250, s1, 56
	s_cselect_b64 s[0:1], -1, 0
	v_writelane_b32 v250, s0, 57
	s_cmp_eq_u32 s46, 0
	s_nop 0
	v_writelane_b32 v250, s1, 58
	s_cselect_b64 s[0:1], -1, 0
	v_writelane_b32 v250, s0, 59
	s_nop 1
	v_writelane_b32 v250, s1, 60
	s_lshl_b32 s0, s46, 8
	s_add_u32 s0, s20, s0
	s_addc_u32 s1, s21, 0
	s_add_u32 s2, s0, 0x1400
	s_addc_u32 s3, s1, 0
	v_writelane_b32 v250, s2, 61
	s_add_u32 s0, s0, 0x2400
	s_addc_u32 s1, s1, 0
	v_writelane_b32 v250, s3, 62
	v_writelane_b32 v250, s0, 63
	v_readlane_b32 s12, v249, 22
	v_readlane_b32 s14, v249, 24
	v_writelane_b32 v251, s1, 0
	s_add_u32 s0, s8, 0x4400
	s_addc_u32 s1, s9, 0
	v_writelane_b32 v251, s0, 1
	v_readlane_b32 s15, v249, 25
	v_readlane_b32 s13, v249, 23
	v_writelane_b32 v251, s1, 2
	s_add_u32 s0, s8, 0x4500
	s_addc_u32 s1, s9, 0
	v_writelane_b32 v251, s0, 3
	v_readlane_b32 s16, v249, 26
	v_readlane_b32 s17, v249, 27
	v_writelane_b32 v251, s1, 4
	s_and_b32 s0, s28, 1
	s_cmp_eq_u32 s0, 0
	v_writelane_b32 v251, s0, 5
	s_cselect_b64 s[0:1], -1, 0
	v_writelane_b32 v251, s0, 6
	s_cmpk_lt_i32 s28, 0x1000
	v_readlane_b32 s18, v249, 28
	v_writelane_b32 v251, s1, 7
	s_cselect_b64 s[0:1], -1, 0
	v_writelane_b32 v251, s0, 8
	s_ashr_i32 s6, s28, 1
	s_lshl_b32 s59, s10, 2
	v_writelane_b32 v251, s1, 9
	s_lshl_b32 s0, s28, 6
	s_and_b32 s7, s0, 64
	v_writelane_b32 v251, s0, 10
	s_add_u32 s0, s14, 0x1000
	s_addc_u32 s1, s15, 0
	v_writelane_b32 v251, s0, 11
	v_readlane_b32 s19, v249, 29
	v_readlane_b32 s20, v249, 30
	v_writelane_b32 v251, s1, 12
	s_abs_i32 s0, s10
	v_cvt_f32_u32_e32 v0, s0
	s_sub_i32 s1, 0, s0
	v_readlane_b32 s21, v249, 31
	v_readlane_b32 s22, v249, 32
	v_rcp_iflag_f32_e32 v0, v0
	v_readlane_b32 s23, v249, 33
	v_readlane_b32 s24, v249, 34
	v_readlane_b32 s25, v249, 35
	v_mul_f32_e32 v0, 0x4f7ffffe, v0
	v_cvt_u32_f32_e32 v0, v0
	v_readlane_b32 s26, v249, 36
	v_readlane_b32 s27, v249, 37
	v_readfirstlane_b32 s2, v0
	s_mul_i32 s1, s1, s2
	s_mul_hi_u32 s1, s2, s1
	s_add_i32 s2, s2, s1
	s_mul_hi_u32 s1, s2, 0x448
	s_mul_i32 s1, s1, s0
	s_sub_i32 s1, 0x448, s1
	s_sub_i32 s2, s1, s0
	s_cmp_ge_u32 s1, s0
	s_cselect_b32 s1, s2, s1
	s_sub_i32 s2, s1, s0
	s_cmp_ge_u32 s1, s0
	s_cselect_b32 s2, s2, s1
	s_sub_i32 s4, 0x448, s2
	s_cmp_lg_u32 s2, 0
	s_cselect_b64 s[0:1], -1, 0
	s_lshl_b32 s5, s2, 1
	s_cmp_le_i32 s5, s10
	s_cselect_b64 s[2:3], -1, 0
	s_and_b64 s[0:1], s[0:1], s[2:3]
	s_and_b64 s[2:3], s[0:1], exec
	s_cselect_b32 s62, s4, 0x448
	s_cmp_lt_i32 s28, s62
	s_cselect_b64 s[2:3], -1, 0
	v_writelane_b32 v251, s2, 13
	s_cmp_lt_i32 s28, s5
	s_nop 0
	v_writelane_b32 v251, s3, 14
	s_cselect_b64 s[2:3], -1, 0
	s_and_b64 s[0:1], s[0:1], s[2:3]
	v_writelane_b32 v251, s0, 15
	s_add_i32 s4, s4, s6
	s_nop 0
	v_writelane_b32 v251, s1, 16
	s_lshr_b32 s0, s6, 3
	s_and_b32 s1, s6, 7
	s_mul_i32 s1, s1, 0x89
	s_add_i32 s4, s1, s0
	s_addk_i32 s4, 0x80
	s_mul_hi_i32 s0, s4, 0x77975b9
	s_lshr_b32 s1, s0, 31
	s_ashr_i32 s0, s0, 2
	s_add_i32 s0, s0, s1
	s_mul_i32 s1, s0, 0x89
	s_sub_i32 s1, s4, s1
	v_writelane_b32 v251, s6, 17
	s_lshl_b32 s1, s1, 7
	s_lshl_b32 s0, s0, 7
	v_writelane_b32 v251, s1, 18
	s_or_b32 s0, s0, s7
	v_writelane_b32 v251, s7, 19
	s_ashr_i32 s1, s0, 31
	v_writelane_b32 v251, s0, 20
	s_nop 1
	v_writelane_b32 v251, s1, 21
	s_add_u32 s0, s8, 0x1cdc0c00
	v_writelane_b32 v251, s0, 22
	s_addc_u32 s0, s9, 0
	v_writelane_b32 v251, s0, 23
	s_add_u32 s0, s8, 0x1d69c000
	v_writelane_b32 v251, s0, 24
	s_addc_u32 s0, s9, 0
	v_writelane_b32 v251, s0, 25
	s_lshl_b32 s0, s28, 3
	v_writelane_b32 v251, s0, 26
	s_lshl_b64 s[0:1], s[28:29], 12
	s_add_u32 s2, s0, 0x4000000
	s_addc_u32 s3, s1, 0
	v_writelane_b32 v251, s2, 27
	s_nop 1
	v_writelane_b32 v251, s3, 28
	s_lshl_b64 s[2:3], s[28:29], 11
	s_add_u32 s2, s8, s2
	s_addc_u32 s3, s9, s3
	v_writelane_b32 v251, s2, 29
	s_add_u32 s0, s0, 0x800000
	s_addc_u32 s1, s1, 0
	v_writelane_b32 v251, s3, 30
	v_writelane_b32 v251, s0, 31
	s_mov_b64 s[8:9], -1
	s_mov_b32 s2, s91
	v_writelane_b32 v251, s1, 32
	s_mul_i32 s0, s11, s10
	s_mul_i32 s81, s0, s33
	s_movk_i32 s0, 0x1e00
	s_addk_i32 s0, 0x80
	v_writelane_b32 v251, s0, 33
	s_mov_b32 s0, 0xcb00
	s_addk_i32 s0, 0x80
	v_writelane_b32 v251, s0, 34
	s_mov_b32 s0, 0xc300
	s_addk_i32 s0, 0x80
	v_writelane_b32 v251, s0, 35
	v_writelane_b32 v251, s96, 36
	s_mov_b32 s33, 0x3e38aa3b
	s_nop 0
	v_writelane_b32 v251, s97, 37
	v_writelane_b32 v251, s59, 38
	v_writelane_b32 v251, s62, 39
	v_writelane_b32 v251, s81, 40
	s_branch .LBB0_195

; template <int NF>
; DI void merge_tile(const Params& p, int layer, int brow, int bcol, bool& first, bool hasNext, int nbrow, int nbcol) {
;   const int tid = get_tid(), wid = __builtin_amdgcn_readfirstlane(tid >> 6), lane = tid & 63, wr = wid >> 1, wc = wid & 1, fr = lane & 15, fq = lane >> 4;
;   const bfr* gmb = (const bfr*)(p.ws + W_GM);
;   bfr* merged = (bfr*)(p.ws + W_HN);
;   unsigned tot[4][NF][2];
; #pragma unroll
;   for (int m = 0; m < 4; ++m)
; #pragma unroll
;     for (int n = 0; n < NF; ++n) { tot[m][n][0] = 0u; tot[m][n][1] = 0u; }
; #pragma unroll 1
;   for (int br = 0; br < 3; ++br) {
;     const bfr* A = (const bfr*)(p.ws + (br == 0 ? W_GA : (br == 1 ? W_GB : W_GC)));
;     const bfr* Bt = (const bfr*)(p.ws + W_WBT) + (long)(layer * 3 + br) * 1024 * 512;
;     const bfr* nA = (const bfr*)(p.ws + (br == 0 ? W_GB : (br == 1 ? W_GC : W_GA)));
;     const bfr* nBt = (const bfr*)(p.ws + W_WBT) + (long)(layer * 3 + (br == 2 ? 0 : br + 1)) * 1024 * 512;
;     const bool nx = br < 2 || hasNext;
;     f32x4 acc[4][NF];
; #pragma unroll
;     for (int m = 0; m < 4; ++m)
; #pragma unroll
;       for (int n = 0; n < NF; ++n) acc[m][n] = f32x4{0.f, 0.f, 0.f, 0.f};
;     gemm128<NF>(A, 512, Bt, 512, 512, brow, bcol, smem, acc, true, first, nx ? (br < 2 ? brow : nbrow) : -1, br < 2 ? bcol : nbcol, nA, nBt);
;     first = false;
; #pragma unroll
;     for (int m = 0; m < 4; ++m) {
;       const int row0 = brow + wr * 64 + m * 16 + fq * 4;
;       if (row0 < ROWS) {
; #pragma unroll
;         for (int n = 0; n < NF; ++n) {
;           const int col = bcol + wc * (NF * 16) + n * 16 + fr;
;           const bfr* gp = gmb + (long)row0 * 3072 + br * 1024 + col;
; DI void phase_merge(const Params& p, int layer, char*) {
;     ...
;   for (int tile = blockIdx.x; tile < lim; tile += G) {
;     const int tn = tile / NTM, tm = tile % NTM;
;     const int t2 = tile + G;
;     const bool hasNext = t2 < lim;
;     merge_tile<4>(p, layer, tm * 128, tn * 128, first, hasNext, (t2 % NTM) * 128, (t2 / NTM) * 128);
.LBB0_4958:
	s_bfe_u32 s0, s43, 0x30003
	s_mul_i32 s0, s0, 0x89
	s_and_b32 s100, s43, 7
	s_add_i32 s0, s0, s100
	s_lshr_b32 s100, s43, 6
	s_lshl3_add_u32 s100, s100, s0
	s_add_i32 s1, s43, s90
	s_bfe_u32 s0, s1, 0x30003
	s_mul_i32 s0, s0, 0x89
	s_and_b32 s101, s1, 7
	s_add_i32 s0, s0, s101
	s_lshr_b32 s101, s1, 6
	s_lshl3_add_u32 s101, s101, s0
	s_mul_hi_i32 s0, s100, 0x77975b9
	s_lshr_b32 s1, s0, 31
	s_ashr_i32 s0, s0, 2
	s_add_i32 s19, s0, s1
	s_mul_i32 s0, s19, 0x89
	s_mov_b32 s18, s100
	s_sub_i32 s0, s100, s0
	s_add_i32 s43, s43, s90
	s_cmp_ge_i32 s43, s38
	s_cselect_b64 s[14:15], -1, 0
	s_lshl_b32 s17, s0, 7
	s_mul_hi_i32 s0, s101, 0x77975b9
	s_lshr_b32 s1, s0, 31
	s_ashr_i32 s0, s0, 2
	s_add_i32 s0, s0, s1
	s_mul_i32 s1, s0, 0x89
	v_mov_b32_e32 v0, v158
	s_sub_i32 s1, s101, s1
	s_lshl_b32 s45, s0, 7
	s_lshl_b32 s16, s19, 7
	v_readfirstlane_b32 s0, v0
	s_lshl_b32 s1, s1, 7
	s_and_b32 s44, s0, 64
	s_cmp_lt_i32 s43, s38
	s_cselect_b32 s46, s1, -1
	s_ashr_i32 s0, s0, 1
	v_and_b32_e32 v65, 15, v0
	s_and_b32 s20, s0, 0xffffffc0
	v_lshrrev_b32_e32 v0, 2, v0
	s_lshl_b32 s18, s18, 7
	v_and_b32_e32 v0, 12, v0
	s_add_i32 s18, s18, s20
	s_add_i32 s0, s20, s17
	s_waitcnt vmcnt(0)
	v_or_b32_e32 v4, s18, v0
	s_or_b32 s18, s16, s44
	v_or_b32_e32 v64, s0, v0
	v_or_b32_e32 v0, s18, v65
	s_mul_i32 s20, s19, 0x4480
	v_ashrrev_i32_e32 v1, 31, v0
	v_subrev_u32_e32 v2, s20, v4
	v_lshlrev_b64 v[0:1], 1, v[0:1]
	v_mad_i64_i32 v[2:3], s[18:19], v2, s61, v[0:1]
	v_lshl_add_u64 v[66:67], s[10:11], 0, v[2:3]
	v_or_b32_e32 v2, 16, v4
	v_subrev_u32_e32 v2, s20, v2
	v_mad_i64_i32 v[2:3], s[18:19], v2, s61, v[0:1]
	v_lshl_add_u64 v[68:69], s[10:11], 0, v[2:3]
	v_or_b32_e32 v2, 32, v4
	v_subrev_u32_e32 v2, s20, v2
	v_mad_i64_i32 v[2:3], s[18:19], v2, s61, v[0:1]
	s_movk_i32 s0, 0x4430
	v_lshl_add_u64 v[70:71], s[10:11], 0, v[2:3]
	v_or_b32_e32 v2, 48, v4
	v_cmp_gt_i32_e64 s[4:5], s0, v64
	s_movk_i32 s0, 0x4420
	v_subrev_u32_e32 v2, s20, v2
	v_cmp_gt_i32_e64 s[2:3], s0, v64
	s_movk_i32 s0, 0x4410
	v_mad_i64_i32 v[0:1], s[18:19], v2, s61, v[0:1]
	v_cmp_gt_i32_e64 s[6:7], s79, v64
	v_cmp_gt_i32_e64 s[0:1], s0, v64
	v_lshl_add_u64 v[72:73], s[10:11], 0, v[0:1]
	v_mov_b32_e32 v106, 0
	s_mov_b64 s[18:19], 0
	s_mov_b32 s47, 0
	v_mov_b32_e32 v85, 0
	v_mov_b32_e32 v78, 0
	v_mov_b32_e32 v86, 0
	v_mov_b32_e32 v79, 0
	v_mov_b32_e32 v84, 0
	v_mov_b32_e32 v83, 0
	v_mov_b32_e32 v80, 0
	v_mov_b32_e32 v107, 0
	v_mov_b32_e32 v92, 0
	v_mov_b32_e32 v81, 0
	v_mov_b32_e32 v93, 0
	v_mov_b32_e32 v82, 0
	v_mov_b32_e32 v91, 0
	v_mov_b32_e32 v90, 0
	v_mov_b32_e32 v87, 0
	v_mov_b32_e32 v108, 0
	v_mov_b32_e32 v99, 0
	v_mov_b32_e32 v88, 0
	v_mov_b32_e32 v100, 0
	v_mov_b32_e32 v89, 0
	v_mov_b32_e32 v98, 0
	v_mov_b32_e32 v97, 0
	v_mov_b32_e32 v94, 0
	v_mov_b32_e32 v109, 0
	v_mov_b32_e32 v104, 0
	v_mov_b32_e32 v95, 0
	v_mov_b32_e32 v105, 0
	v_mov_b32_e32 v96, 0
	v_mov_b32_e32 v103, 0
	v_mov_b32_e32 v102, 0
	v_mov_b32_e32 v101, 0
	s_branch .LBB0_4960

; template <int NF>
; DI void merge_tile(const Params& p, int layer, int brow, int bcol, bool& first, bool hasNext, int nbrow, int nbcol) {
;   const int tid = get_tid(), wid = __builtin_amdgcn_readfirstlane(tid >> 6), lane = tid & 63, wr = wid >> 1, wc = wid & 1, fr = lane & 15, fq = lane >> 4;
;   const bfr* gmb = (const bfr*)(p.ws + W_GM);
;   bfr* merged = (bfr*)(p.ws + W_HN);
;   unsigned tot[4][NF][2];
; #pragma unroll
;   for (int m = 0; m < 4; ++m)
; #pragma unroll
;     for (int n = 0; n < NF; ++n) { tot[m][n][0] = 0u; tot[m][n][1] = 0u; }
; #pragma unroll 1
;   for (int br = 0; br < 3; ++br) {
;     const bfr* A = (const bfr*)(p.ws + (br == 0 ? W_GA : (br == 1 ? W_GB : W_GC)));
;     const bfr* Bt = (const bfr*)(p.ws + W_WBT) + (long)(layer * 3 + br) * 1024 * 512;
;     const bfr* nA = (const bfr*)(p.ws + (br == 0 ? W_GB : (br == 1 ? W_GC : W_GA)));
;     const bfr* nBt = (const bfr*)(p.ws + W_WBT) + (long)(layer * 3 + (br == 2 ? 0 : br + 1)) * 1024 * 512;
;     const bool nx = br < 2 || hasNext;
;     f32x4 acc[4][NF];
; #pragma unroll
;     for (int m = 0; m < 4; ++m)
; #pragma unroll
;       for (int n = 0; n < NF; ++n) acc[m][n] = f32x4{0.f, 0.f, 0.f, 0.f};
;     gemm128<NF>(A, 512, Bt, 512, 512, brow, bcol, smem, acc, true, first, nx ? (br < 2 ? brow : nbrow) : -1, br < 2 ? bcol : nbcol, nA, nBt);
;     first = false;
; #pragma unroll
;     for (int m = 0; m < 4; ++m) {
;       const int row0 = brow + wr * 64 + m * 16 + fq * 4;
;       if (row0 < ROWS) {
; #pragma unroll
;         for (int n = 0; n < NF; ++n) {
;           const int col = bcol + wc * (NF * 16) + n * 16 + fr;
;           const bfr* gp = gmb + (long)row0 * 3072 + br * 1024 + col;
; DI void phase_merge(const Params& p, int layer, char*) {
;     ...
;   if (split && (int)blockIdx.x < 2 * rem) {
;     const int tile = nfull + ((int)blockIdx.x >> 1), half = blockIdx.x & 1;
;     const int tn = tile / NTM, tm = tile % NTM;
;     bool f2 = true;
;     merge_tile<2>(p, layer, tm * 128, tn * 128 + half * 64, f2, false, 0, 0);
.LBB0_4982:
	v_readlane_b32 s0, v249, 54
	v_readlane_b32 s1, v249, 55
	s_cmp_lt_i32 s0, s37
	s_cselect_b64 s[0:1], -1, 0
	s_and_b64 s[0:1], s[12:13], s[0:1]
	s_and_b64 vcc, exec, s[0:1]
	s_cbranch_vccz .LBB0_5008
	v_readlane_b32 s0, v251, 17
	s_lshr_b32 s1, s0, 3
	s_and_b32 s0, s0, 7
	s_mul_i32 s0, s0, 0x89
	s_add_i32 s36, s0, s1
	s_addk_i32 s36, 0x80
	s_mul_hi_i32 s0, s36, 0x77975b9
	s_lshr_b32 s1, s0, 31
	s_ashr_i32 s0, s0, 2
	s_add_i32 s14, s0, s1
	s_mul_i32 s0, s14, 0x89
	s_sub_i32 s0, s36, s0
	s_lshl_b32 s13, s0, 7
	s_lshl_b32 s0, s14, 7
	v_readlane_b32 s1, v251, 19
	v_mov_b32_e32 v0, v158
	s_or_b32 s12, s0, s1
	s_mul_i32 s18, s14, 0x4480
	v_readfirstlane_b32 s0, v0
	s_ashr_i32 s1, s0, 1
	s_and_b32 s15, s1, 0xffffffc0
	s_lshr_b32 s0, s0, 1
	s_add_i32 s1, s15, s13
	s_and_b32 s26, s0, 32
	s_add_u32 s27, s10, 0x1dc8400
	v_and_b32_e32 v33, 15, v0
	v_lshrrev_b32_e32 v0, 2, v0
	s_addc_u32 s28, s11, 0
	s_lshl_b32 s16, s36, 7
	v_and_b32_e32 v0, 12, v0
	s_add_i32 s16, s16, s15
	s_add_i32 s14, s12, s26
	v_or_b32_e32 v32, s1, v0
	s_waitcnt vmcnt(0)
	v_or_b32_e32 v4, s16, v0
	v_add_u32_e32 v0, s14, v33
	v_ashrrev_i32_e32 v1, 31, v0
	v_subrev_u32_e32 v2, s18, v4
	v_lshlrev_b64 v[0:1], 1, v[0:1]
	v_mad_i64_i32 v[2:3], s[14:15], v2, s61, v[0:1]
	v_readlane_b32 s20, v249, 0
	v_readlane_b32 s21, v249, 1
	s_add_u32 s14, s20, s8
	s_addc_u32 s15, s21, s9
	v_lshl_add_u64 v[34:35], s[14:15], 0, v[2:3]
	v_or_b32_e32 v2, 16, v4
	v_subrev_u32_e32 v2, s18, v2
	v_mad_i64_i32 v[2:3], s[16:17], v2, s61, v[0:1]
	v_lshl_add_u64 v[36:37], s[14:15], 0, v[2:3]
	v_or_b32_e32 v2, 32, v4
	v_subrev_u32_e32 v2, s18, v2
	v_mad_i64_i32 v[2:3], s[16:17], v2, s61, v[0:1]
	s_movk_i32 s0, 0x4430
	v_lshl_add_u64 v[38:39], s[14:15], 0, v[2:3]
	v_or_b32_e32 v2, 48, v4
	v_cmp_gt_i32_e64 s[4:5], s0, v32
	s_movk_i32 s0, 0x4420
	v_subrev_u32_e32 v2, s18, v2
	v_cmp_gt_i32_e64 s[2:3], s0, v32
	s_movk_i32 s0, 0x4410
	v_mad_i64_i32 v[0:1], s[16:17], v2, s61, v[0:1]
	v_cmp_gt_i32_e64 s[6:7], s79, v32
	v_cmp_gt_i32_e64 s[0:1], s0, v32
	v_lshl_add_u64 v[40:41], s[14:15], 0, v[0:1]
	v_mov_b32_e32 v54, 0
	s_mov_b64 s[20:21], -1
	s_mov_b64 s[14:15], 0
	s_mov_b32 s29, 0
	v_mov_b32_e32 v42, 0
	v_mov_b32_e32 v45, 0
	v_mov_b32_e32 v44, 0
	v_mov_b32_e32 v55, 0
	v_mov_b32_e32 v43, 0
	v_mov_b32_e32 v48, 0
	v_mov_b32_e32 v47, 0
	v_mov_b32_e32 v56, 0
	v_mov_b32_e32 v46, 0
	v_mov_b32_e32 v51, 0
	v_mov_b32_e32 v50, 0
	v_mov_b32_e32 v57, 0
	v_mov_b32_e32 v49, 0
	v_mov_b32_e32 v53, 0
	v_mov_b32_e32 v52, 0
	v_readlane_b32 s22, v249, 2
	v_readlane_b32 s23, v249, 3
	s_branch .LBB0_4985

;   const int tid = get_tid(), wid = __builtin_amdgcn_readfirstlane(tid >> 6), lane = tid & 63, wr = wid >> 1, wc = wid & 1, fr = lane & 15, fq = lane >> 4;
;   const int r0 = tid >> 3;
;   const int cg = ((tid & 7) ^ (r0 & 7)) * 8;
;   const bfr* ga = A + (long)(brow + r0) * lda + cg;
;   const bfr* gb = Bt + (long)(bcol + r0) * ldb + cg;
;   const long a32 = (long)32 * lda, b32 = (long)32 * ldb;
;   const int nk = K / 64;
;   auto stage = [&](int kt, int buf) {
;     char* SA = smem + buf * 32768;
;     char* SB = SA + 16384;
; #pragma unroll
;     for (int i = 0; i < 4; ++i)
;       __builtin_amdgcn_global_load_lds((const unsigned*)(ga + i * a32 + kt * 64), (unsigned*)(SA + tid * 16 + i * 4096), 16, 0, 0);
; #pragma unroll
;     for (int i = 0; i < NF; ++i)
;       __builtin_amdgcn_global_load_lds((const unsigned*)(gb + i * b32 + kt * 64), (unsigned*)(SB + tid * 16 + i * 4096), 16, 0, 0);
;   };
;   if (!chained || first) {
;     asm volatile("s_waitcnt vmcnt(0)" ::: "memory");
;     __syncthreads();
;     stage(0, 0);
; DI void phase_out(const Params& p, int layer, char*) {
;     ...
;   for (int tile = blockIdx.x; tile < lim; tile += G) {
;     const int tn = tile / NTM, tm = tile % NTM;
;     const int t2 = tile + G;
;     out_tile<4>(p, layer, tm * 128, tn * 128, first, t2 < lim, (t2 % NTM) * 128, (t2 / NTM) * 128);
.LBB0_5100:
	s_bfe_u32 s10, s14, 0x30003
	s_mul_i32 s10, s10, 0x89
	s_and_b32 s100, s14, 7
	s_add_i32 s10, s10, s100
	s_lshr_b32 s100, s14, 6
	s_lshl3_add_u32 s100, s100, s10
	s_mul_hi_i32 s10, s100, 0x77975b9
	s_lshr_b32 s11, s10, 31
	s_ashr_i32 s10, s10, 2
	s_add_i32 s10, s10, s11
	s_mul_i32 s11, s10, 0x89
	v_ashrrev_i32_e32 v71, 3, v4
	s_sub_i32 s11, s100, s11
	v_xor_b32_e32 v5, v71, v4
	s_lshl_b32 s11, s11, 7
	s_lshl_b32 s10, s10, 7
	v_lshlrev_b32_e32 v0, 3, v5
	v_and_b32_e32 v8, 56, v0
	v_add_u32_e32 v0, s11, v71
	v_add_u32_e32 v2, s10, v71
	v_ashrrev_i32_e32 v1, 31, v0
	v_ashrrev_i32_e32 v3, 31, v2
	v_lshlrev_b64 v[0:1], 11, v[0:1]
	v_lshlrev_b64 v[2:3], 11, v[2:3]
	s_andn2_b64 vcc, exec, s[8:9]
	v_lshlrev_b32_e32 v64, 1, v8
	s_cbranch_vccnz .LBB0_5102
	v_add_u32_e32 v7, 0x80, v6
	v_lshl_add_u64 v[8:9], s[4:5], 0, v[0:1]
	v_mov_b32_e32 v65, v129
	v_readfirstlane_b32 s8, v7
	v_add_u32_e32 v14, 0x1000, v7
	v_lshl_add_u64 v[8:9], v[8:9], 0, v[64:65]
	s_mov_b32 m0, s8
	s_mov_b64 s[18:19], 0x10000
	v_readfirstlane_b32 s8, v14
	v_add_u32_e32 v14, 0x2000, v7
	s_waitcnt vmcnt(0)
	s_barrier
	global_load_lds_dwordx4 v[8:9], off
	v_lshl_add_u64 v[12:13], v[8:9], 0, s[18:19]
	s_mov_b32 m0, s8
	s_mov_b64 s[20:21], 0x20000
	v_readfirstlane_b32 s8, v14
	global_load_lds_dwordx4 v[12:13], off
	v_lshl_add_u64 v[12:13], v[8:9], 0, s[20:21]
	s_mov_b32 m0, s8
	s_mov_b64 s[22:23], 0x30000
	global_load_lds_dwordx4 v[12:13], off
	v_add_u32_e32 v12, 0x3000, v7
	v_lshl_add_u64 v[8:9], v[8:9], 0, s[22:23]
	v_readfirstlane_b32 s8, v12
	s_mov_b32 m0, s8
	v_lshl_add_u64 v[10:11], s[2:3], 0, v[2:3]
	global_load_lds_dwordx4 v[8:9], off
	v_add_u32_e32 v8, 0x4000, v7
	v_add_u32_e32 v12, 0x5000, v7
	v_readfirstlane_b32 s8, v8
	v_lshl_add_u64 v[10:11], v[10:11], 0, v[64:65]
	s_mov_b32 m0, s8
	v_readfirstlane_b32 s8, v12
	v_add_u32_e32 v12, 0x6000, v7
	global_load_lds_dwordx4 v[10:11], off
	v_lshl_add_u64 v[8:9], v[10:11], 0, s[18:19]
	s_mov_b32 m0, s8
	v_readfirstlane_b32 s8, v12
	v_add_u32_e32 v7, 0x7000, v7
	global_load_lds_dwordx4 v[8:9], off
	v_lshl_add_u64 v[8:9], v[10:11], 0, s[20:21]
	s_mov_b32 m0, s8
	v_readfirstlane_b32 s8, v7
	global_load_lds_dwordx4 v[8:9], off
	v_lshl_add_u64 v[8:9], v[10:11], 0, s[22:23]
	s_mov_b32 m0, s8
	v_mov_b32_e32 v7, v6
	global_load_lds_dwordx4 v[8:9], off

;     ...
;   for (int kt = 0; kt < nk; ++kt) {
;     asm volatile("s_waitcnt vmcnt(0)" ::: "memory");
;     __builtin_amdgcn_s_barrier();
;     if (kt + 1 < nk) stage(kt + 1, (kt + 1) & 1);
;     else if (chained && nbrow >= 0) {
;       const bfr* na = (nA ? nA : A) + (long)(nbrow + r0) * lda + cg;
;       const bfr* nb = (nBt ? nBt : Bt) + (long)(nbcol + r0) * ldb + cg;
; #pragma unroll
;       for (int i = 0; i < 4; ++i)
;         __builtin_amdgcn_global_load_lds((const unsigned*)(na + i * a32), (unsigned*)(smem + tid * 16 + i * 4096), 16, 0, 0);
; #pragma unroll
;       for (int i = 0; i < NF; ++i)
;         __builtin_amdgcn_global_load_lds((const unsigned*)(nb + i * b32), (unsigned*)(smem + 16384 + tid * 16 + i * 4096), 16, 0, 0);
;     }
;     const unsigned bo = (kt & 1) * 32768;
;     bf16x8 af[2][4], bfg[2][4];
;     if (NF == 4) {
;       asm volatile(
;           "ds_read_b128 %0, %16\n\tds_read_b128 %1, %16 offset:2048\n\tds_read_b128 %2, %16 offset:4096\n\tds_read_b128 %3, %16 offset:6144\n\t"
;           "ds_read_b128 %4, %17\n\tds_read_b128 %5, %17 offset:2048\n\tds_read_b128 %6, %17 offset:4096\n\tds_read_b128 %7, %17 offset:6144\n\t"
;           "ds_read_b128 %8, %18\n\tds_read_b128 %9, %18 offset:2048\n\tds_read_b128 %10, %18 offset:4096\n\tds_read_b128 %11, %18 offset:6144\n\t"
;           "ds_read_b128 %12, %19\n\tds_read_b128 %13, %19 offset:2048\n\tds_read_b128 %14, %19 offset:4096\n\tds_read_b128 %15, %19 offset:6144\n\t"
;           "s_waitcnt lgkmcnt(0)"
;           : "=&v"(af[0][0]), "=&v"(af[0][1]), "=&v"(af[0][2]), "=&v"(af[0][3]), "=&v"(bfg[0][0]), "=&v"(bfg[0][1]), "=&v"(bfg[0][2]), "=&v"(bfg[0][3]),
;             "=&v"(af[1][0]), "=&v"(af[1][1]), "=&v"(af[1][2]), "=&v"(af[1][3]), "=&v"(bfg[1][0]), "=&v"(bfg[1][1]), "=&v"(bfg[1][2]), "=&v"(bfg[1][3])
;           : "v"(arow + sw0 + bo), "v"(brw + sw0 + bo), "v"(arow + sw1 + bo), "v"(brw + sw1 + bo)
;           : "memory");
;     } else {
;       asm volatile(
;           "ds_read_b128 %0, %12\n\tds_read_b128 %1, %12 offset:2048\n\tds_read_b128 %2, %12 offset:4096\n\tds_read_b128 %3, %12 offset:6144\n\t"
;           "ds_read_b128 %4, %13\n\tds_read_b128 %5, %13 offset:2048\n\t"
;           "ds_read_b128 %6, %14\n\tds_read_b128 %7, %14 offset:2048\n\tds_read_b128 %8, %14 offset:4096\n\tds_read_b128 %9, %14 offset:6144\n\t"
.LBB0_5103:
	s_add_i32 s17, s16, 0x8000
	s_and_b32 s18, s17, 0x8000
	v_add_u32_e32 v65, s18, v76
	v_lshl_add_u64 v[78:79], v[66:67], 0, s[8:9]
	v_readfirstlane_b32 s18, v65
	v_add_u32_e32 v77, 0x1000, v65
	v_lshl_add_u64 v[80:81], v[78:79], 0, s[52:53]
	s_mov_b32 m0, s18
	v_readfirstlane_b32 s18, v77
	v_add_u32_e32 v77, 0x2000, v65
	s_waitcnt vmcnt(0)
	s_barrier
	global_load_lds_dwordx4 v[80:81], off
	v_lshl_add_u64 v[80:81], v[78:79], 0, s[54:55]
	s_mov_b32 m0, s18
	v_readfirstlane_b32 s18, v77
	v_add_u32_e32 v77, 0x3000, v65
	global_load_lds_dwordx4 v[80:81], off
	v_lshl_add_u64 v[80:81], v[78:79], 0, s[56:57]
	s_mov_b32 m0, s18
	v_readfirstlane_b32 s18, v77
	global_load_lds_dwordx4 v[80:81], off
	v_lshl_add_u64 v[78:79], v[78:79], 0, s[20:21]
	s_mov_b32 m0, s18
	v_add_u32_e32 v77, 0x4000, v65
	global_load_lds_dwordx4 v[78:79], off
	v_lshl_add_u64 v[78:79], v[68:69], 0, s[8:9]
	v_readfirstlane_b32 s18, v77
	v_add_u32_e32 v77, 0x5000, v65
	v_lshl_add_u64 v[80:81], v[78:79], 0, s[22:23]
	s_mov_b32 m0, s18
	v_readfirstlane_b32 s18, v77
	global_load_lds_dwordx4 v[80:81], off
	v_lshl_add_u64 v[80:81], v[78:79], 0, s[24:25]
	s_mov_b32 m0, s18
	s_mov_b64 s[18:19], 0x23e8480
	v_add_u32_e32 v77, 0x6000, v65
	global_load_lds_dwordx4 v[80:81], off
	v_lshl_add_u64 v[80:81], v[78:79], 0, s[18:19]
	v_readfirstlane_b32 s18, v77
	s_mov_b32 m0, s18
	s_mov_b64 s[18:19], 0x23f8480
	v_add_u32_e32 v65, 0x7000, v65
	v_lshl_add_u64 v[78:79], v[78:79], 0, s[18:19]
	v_readfirstlane_b32 s18, v65
	global_load_lds_dwordx4 v[80:81], off
	s_mov_b32 m0, s18
	s_and_b32 s16, s16, 0x8000
	global_load_lds_dwordx4 v[78:79], off
	v_add_u32_e32 v65, s16, v72
	v_add_u32_e32 v77, s16, v73
	v_add_u32_e32 v126, s16, v74
	v_add_u32_e32 v127, s16, v75
	ds_read_b128 v[78:81], v65
	ds_read_b128 v[82:85], v65 offset:2048
	ds_read_b128 v[86:89], v65 offset:4096
	ds_read_b128 v[90:93], v65 offset:6144
	ds_read_b128 v[94:97], v77
	ds_read_b128 v[98:101], v77 offset:2048
	ds_read_b128 v[102:105], v77 offset:4096
	ds_read_b128 v[106:109], v77 offset:6144
	ds_read_b128 v[110:113], v126
	ds_read_b128 v[114:117], v126 offset:2048
	ds_read_b128 v[118:121], v126 offset:4096
	ds_read_b128 v[122:125], v126 offset:6144
	ds_read_b128 v[132:135], v127
	ds_read_b128 v[136:139], v127 offset:2048
	ds_read_b128 v[140:143], v127 offset:4096
	ds_read_b128 v[144:147], v127 offset:6144
	s_waitcnt lgkmcnt(8)
	s_setprio 1
	v_mfma_f32_16x16x32_bf16 v[60:63], v[78:81], v[94:97], v[60:63]
	v_mfma_f32_16x16x32_bf16 v[56:59], v[78:81], v[98:101], v[56:59]
	v_mfma_f32_16x16x32_bf16 v[52:55], v[78:81], v[102:105], v[52:55]
	v_mfma_f32_16x16x32_bf16 v[48:51], v[78:81], v[106:109], v[48:51]
	v_mfma_f32_16x16x32_bf16 v[44:47], v[82:85], v[94:97], v[44:47]
	v_mfma_f32_16x16x32_bf16 v[40:43], v[82:85], v[98:101], v[40:43]
	v_mfma_f32_16x16x32_bf16 v[36:39], v[82:85], v[102:105], v[36:39]
	v_mfma_f32_16x16x32_bf16 v[32:35], v[82:85], v[106:109], v[32:35]
	v_mfma_f32_16x16x32_bf16 v[28:31], v[86:89], v[94:97], v[28:31]
	v_mfma_f32_16x16x32_bf16 v[24:27], v[86:89], v[98:101], v[24:27]
	v_mfma_f32_16x16x32_bf16 v[20:23], v[86:89], v[102:105], v[20:23]
	v_mfma_f32_16x16x32_bf16 v[16:19], v[86:89], v[106:109], v[16:19]
	v_mfma_f32_16x16x32_bf16 v[12:15], v[90:93], v[94:97], v[12:15]
	v_mfma_f32_16x16x32_bf16 v[8:11], v[90:93], v[98:101], v[8:11]
	v_mfma_f32_16x16x32_bf16 v[4:7], v[90:93], v[102:105], v[4:7]
	v_mfma_f32_16x16x32_bf16 v[0:3], v[90:93], v[106:109], v[0:3]
	s_waitcnt lgkmcnt(0)
	v_mfma_f32_16x16x32_bf16 v[60:63], v[110:113], v[132:135], v[60:63]
	v_mfma_f32_16x16x32_bf16 v[56:59], v[110:113], v[136:139], v[56:59]
	v_mfma_f32_16x16x32_bf16 v[52:55], v[110:113], v[140:143], v[52:55]
	v_mfma_f32_16x16x32_bf16 v[48:51], v[110:113], v[144:147], v[48:51]
	v_mfma_f32_16x16x32_bf16 v[44:47], v[114:117], v[132:135], v[44:47]
	v_mfma_f32_16x16x32_bf16 v[40:43], v[114:117], v[136:139], v[40:43]
	v_mfma_f32_16x16x32_bf16 v[36:39], v[114:117], v[140:143], v[36:39]
	v_mfma_f32_16x16x32_bf16 v[32:35], v[114:117], v[144:147], v[32:35]
	v_mfma_f32_16x16x32_bf16 v[28:31], v[118:121], v[132:135], v[28:31]
	v_mfma_f32_16x16x32_bf16 v[24:27], v[118:121], v[136:139], v[24:27]
	v_mfma_f32_16x16x32_bf16 v[20:23], v[118:121], v[140:143], v[20:23]
	v_mfma_f32_16x16x32_bf16 v[16:19], v[118:121], v[144:147], v[16:19]
	v_mfma_f32_16x16x32_bf16 v[12:15], v[122:125], v[132:135], v[12:15]
	v_mfma_f32_16x16x32_bf16 v[8:11], v[122:125], v[136:139], v[8:11]
	v_mfma_f32_16x16x32_bf16 v[4:7], v[122:125], v[140:143], v[4:7]
	v_mfma_f32_16x16x32_bf16 v[0:3], v[122:125], v[144:147], v[0:3]
	s_setprio 0
	s_add_u32 s8, s8, 0x80
	s_addc_u32 s9, s9, 0
	s_cmpk_eq_i32 s8, 0x780
	s_mov_b32 s16, s17
	s_cbranch_scc0 .LBB0_5103
;     ...
;     if (kt + 1 < nk) stage(kt + 1, (kt + 1) & 1);
;     else if (chained && nbrow >= 0) {
;       const bfr* na = (nA ? nA : A) + (long)(nbrow + r0) * lda + cg;
;       const bfr* nb = (nBt ? nBt : Bt) + (long)(nbcol + r0) * ldb + cg;
; #pragma unroll
;       for (int i = 0; i < 4; ++i)
;         __builtin_amdgcn_global_load_lds((const unsigned*)(na + i * a32), (unsigned*)(smem + tid * 16 + i * 4096), 16, 0, 0);
; #pragma unroll
;       for (int i = 0; i < NF; ++i)
;         __builtin_amdgcn_global_load_lds((const unsigned*)(nb + i * b32), (unsigned*)(smem + 16384 + tid * 16 + i * 4096), 16, 0, 0);
;     }
; DI void phase_out(const Params& p, int layer, char*) {
;     ...
;   for (int tile = blockIdx.x; tile < lim; tile += G) {
;     const int tn = tile / NTM, tm = tile % NTM;
;     const int t2 = tile + G;
;     out_tile<4>(p, layer, tm * 128, tn * 128, first, t2 < lim, (t2 % NTM) * 128, (t2 / NTM) * 128);
	v_readlane_b32 s16, v249, 0
	v_readlane_b32 s18, v249, 2
	s_add_i32 s14, s14, s18
	v_readlane_b32 s17, v249, 1
	s_bfe_u32 s16, s14, 0x30003
	s_mul_i32 s16, s16, 0x89
	s_and_b32 s101, s14, 7
	s_add_i32 s16, s16, s101
	s_lshr_b32 s101, s14, 6
	s_lshl3_add_u32 s101, s101, s16
	s_cmp_ge_i32 s14, s62
	s_mul_hi_i32 s16, s101, 0x77975b9
	s_cselect_b64 s[8:9], -1, 0
	s_lshr_b32 s17, s16, 31
	s_ashr_i32 s16, s16, 2
	s_add_i32 s16, s16, s17
	s_mul_i32 s17, s16, 0x89
	s_sub_i32 s17, s101, s17
	s_lshl_b32 s17, s17, 7
	s_cmp_lt_i32 s14, s62
	s_waitcnt vmcnt(0)
	s_cselect_b32 s17, s17, -1
	s_cmp_lt_i32 s17, 0
	s_mov_b64 s[20:21], 0x20000
	v_readlane_b32 s19, v249, 3
	s_barrier
	s_cbranch_scc1 .LBB0_5106
	v_add_u32_e32 v66, s17, v71
	v_lshl_add_u32 v68, s16, 7, v71
	v_ashrrev_i32_e32 v67, 31, v66
	v_ashrrev_i32_e32 v69, 31, v68
	v_lshlrev_b64 v[68:69], 11, v[68:69]
	v_lshlrev_b64 v[66:67], 11, v[66:67]
	v_lshl_add_u64 v[68:69], s[2:3], 0, v[68:69]
	v_lshl_add_u64 v[66:67], s[4:5], 0, v[66:67]
	v_mov_b32_e32 v65, v129
	v_readfirstlane_b32 s16, v76
	v_add_u32_e32 v77, 0x1000, v76
	v_lshl_add_u64 v[68:69], v[68:69], 0, v[64:65]
	v_lshl_add_u64 v[64:65], v[66:67], 0, v[64:65]
	s_mov_b32 m0, s16
	s_mov_b64 s[18:19], 0x10000
	v_readfirstlane_b32 s16, v77
	v_add_u32_e32 v77, 0x2000, v76
	global_load_lds_dwordx4 v[64:65], off
	v_lshl_add_u64 v[66:67], v[64:65], 0, s[18:19]
	s_mov_b32 m0, s16
	v_readfirstlane_b32 s16, v77
	global_load_lds_dwordx4 v[66:67], off
	v_lshl_add_u64 v[66:67], v[64:65], 0, s[20:21]
	s_mov_b32 m0, s16
	v_add_u32_e32 v71, 0x4000, v76
	global_load_lds_dwordx4 v[66:67], off
	v_add_u32_e32 v66, 0x3000, v76
	s_mov_b64 s[22:23], 0x30000
	v_readfirstlane_b32 s16, v66
	v_lshl_add_u64 v[64:65], v[64:65], 0, s[22:23]
	s_mov_b32 m0, s16
	v_readfirstlane_b32 s16, v71
	v_add_u32_e32 v66, 0x5000, v76
	global_load_lds_dwordx4 v[64:65], off
	s_mov_b32 m0, s16
	v_readfirstlane_b32 s16, v66
	v_add_u32_e32 v66, 0x6000, v76
	global_load_lds_dwordx4 v[68:69], off
	v_lshl_add_u64 v[64:65], v[68:69], 0, s[18:19]
	s_mov_b32 m0, s16
	v_readfirstlane_b32 s16, v66
	v_add_u32_e32 v66, 0x7000, v76
	global_load_lds_dwordx4 v[64:65], off
	v_lshl_add_u64 v[64:65], v[68:69], 0, s[20:21]
	s_mov_b32 m0, s16
	v_readfirstlane_b32 s16, v66
	global_load_lds_dwordx4 v[64:65], off
	v_lshl_add_u64 v[64:65], v[68:69], 0, s[22:23]
	s_mov_b32 m0, s16
	s_nop 0
	global_load_lds_dwordx4 v[64:65], off
